# PEER top-k phase: one static s_setprio 2 for waves 4-7 (the second wave of each SIMD pair) for the duration of the head loop, reset after
# speedup vs baseline: 1.0022x; 1.0022x over previous
.LBB0_1345:
	s_cmp_ge_u32 s62, 64
	s_cbranch_scc0 .Lmy_tprio_skip
	s_setprio 2

.LBB0_1375:
	v_max_u32_dpp v31, v72, v72 row_ror:1 row_mask:0xf bank_mask:0xf bound_ctrl:1
	v_max_u32_dpp v30, v76, v76 row_ror:1 row_mask:0xf bank_mask:0xf bound_ctrl:1
	v_max_u32_dpp v32, v80, v80 row_ror:1 row_mask:0xf bank_mask:0xf bound_ctrl:1
	v_max_u32_dpp v31, v31, v31 row_ror:2 row_mask:0xf bank_mask:0xf bound_ctrl:1
	v_max_u32_dpp v33, v84, v84 row_ror:1 row_mask:0xf bank_mask:0xf bound_ctrl:1
	v_max_u32_dpp v30, v30, v30 row_ror:2 row_mask:0xf bank_mask:0xf bound_ctrl:1
	v_max_u32_dpp v32, v32, v32 row_ror:2 row_mask:0xf bank_mask:0xf bound_ctrl:1
	v_max_u32_dpp v31, v31, v31 row_ror:4 row_mask:0xf bank_mask:0xf bound_ctrl:1
	v_max_u32_dpp v33, v33, v33 row_ror:2 row_mask:0xf bank_mask:0xf bound_ctrl:1
	v_max_u32_dpp v30, v30, v30 row_ror:4 row_mask:0xf bank_mask:0xf bound_ctrl:1
	v_max_u32_dpp v32, v32, v32 row_ror:4 row_mask:0xf bank_mask:0xf bound_ctrl:1
	v_max_u32_dpp v31, v31, v31 row_ror:8 row_mask:0xf bank_mask:0xf bound_ctrl:1
	v_max_u32_dpp v33, v33, v33 row_ror:4 row_mask:0xf bank_mask:0xf bound_ctrl:1
	v_max_u32_dpp v30, v30, v30 row_ror:8 row_mask:0xf bank_mask:0xf bound_ctrl:1
	v_max_u32_dpp v32, v32, v32 row_ror:8 row_mask:0xf bank_mask:0xf bound_ctrl:1
	v_max_u32_dpp v33, v33, v33 row_ror:8 row_mask:0xf bank_mask:0xf bound_ctrl:1
	v_cmp_eq_u32_e64 s[84:85], v72, v31
	v_cmp_eq_u32_e64 s[86:87], v76, v30
	v_cmp_eq_u32_e64 s[88:89], v80, v32
	v_cmp_eq_u32_e64 s[90:91], v84, v33
	s_mov_b64 exec, s[84:85]
	v_pk_mov_b32 v[72:73], v[72:73], v[74:75] op_sel:[1,0] op_sel_hi:[1,0]
	v_pk_mov_b32 v[74:75], v[74:75], v[70:71] op_sel:[1,0] op_sel_hi:[1,0]
	s_mov_b64 exec, s[86:87]
	v_pk_mov_b32 v[76:77], v[76:77], v[78:79] op_sel:[1,0] op_sel_hi:[1,0]
	v_pk_mov_b32 v[78:79], v[78:79], v[70:71] op_sel:[1,0] op_sel_hi:[1,0]
	s_mov_b64 exec, s[88:89]
	v_pk_mov_b32 v[80:81], v[80:81], v[82:83] op_sel:[1,0] op_sel_hi:[1,0]
	v_pk_mov_b32 v[82:83], v[82:83], v[70:71] op_sel:[1,0] op_sel_hi:[1,0]
	s_mov_b64 exec, s[90:91]
	v_pk_mov_b32 v[84:85], v[84:85], v[86:87] op_sel:[1,0] op_sel_hi:[1,0]
	v_pk_mov_b32 v[86:87], v[86:87], v[70:71] op_sel:[1,0] op_sel_hi:[1,0]
	s_lshl_b64 exec, s[78:79], s40
	s_add_i32 s40, s40, 1
	v_pk_mov_b32 v[4:5], v[32:33], v[32:33] op_sel:[1,0] op_sel_hi:[1,0]
	v_pk_mov_b32 v[6:7], v[30:31], v[30:31] op_sel:[1,0] op_sel_hi:[1,0]
	s_mov_b64 exec, -1
	s_cmp_lg_u32 s40, 8
	s_cbranch_scc1 .LBB0_1375
	v_max_u32_dpp v31, v72, v72 row_ror:1 row_mask:0xf bank_mask:0xf bound_ctrl:1
	v_max_u32_dpp v30, v76, v76 row_ror:1 row_mask:0xf bank_mask:0xf bound_ctrl:1
	v_max_u32_dpp v32, v80, v80 row_ror:1 row_mask:0xf bank_mask:0xf bound_ctrl:1
	v_max_u32_dpp v31, v31, v31 row_ror:2 row_mask:0xf bank_mask:0xf bound_ctrl:1
	v_max_u32_dpp v33, v84, v84 row_ror:1 row_mask:0xf bank_mask:0xf bound_ctrl:1
	v_max_u32_dpp v30, v30, v30 row_ror:2 row_mask:0xf bank_mask:0xf bound_ctrl:1
	v_max_u32_dpp v32, v32, v32 row_ror:2 row_mask:0xf bank_mask:0xf bound_ctrl:1
	v_max_u32_dpp v31, v31, v31 row_ror:4 row_mask:0xf bank_mask:0xf bound_ctrl:1
	v_max_u32_dpp v33, v33, v33 row_ror:2 row_mask:0xf bank_mask:0xf bound_ctrl:1
	v_max_u32_dpp v30, v30, v30 row_ror:4 row_mask:0xf bank_mask:0xf bound_ctrl:1
	v_max_u32_dpp v32, v32, v32 row_ror:4 row_mask:0xf bank_mask:0xf bound_ctrl:1
	v_max_u32_dpp v31, v31, v31 row_ror:8 row_mask:0xf bank_mask:0xf bound_ctrl:1
	v_max_u32_dpp v33, v33, v33 row_ror:4 row_mask:0xf bank_mask:0xf bound_ctrl:1
	v_max_u32_dpp v30, v30, v30 row_ror:8 row_mask:0xf bank_mask:0xf bound_ctrl:1
	v_max_u32_dpp v32, v32, v32 row_ror:8 row_mask:0xf bank_mask:0xf bound_ctrl:1
	v_max_u32_dpp v33, v33, v33 row_ror:8 row_mask:0xf bank_mask:0xf bound_ctrl:1
	v_cmp_eq_u32_e64 s[84:85], v72, v31
	v_cmp_eq_u32_e64 s[86:87], v76, v30
	v_cmp_eq_u32_e64 s[88:89], v80, v32
	v_cmp_eq_u32_e64 s[90:91], v84, v33
	s_mov_b64 exec, s[84:85]
	v_pk_mov_b32 v[72:73], v[72:73], v[74:75] op_sel:[1,0] op_sel_hi:[1,0]
	v_pk_mov_b32 v[74:75], v[74:75], v[70:71] op_sel:[1,0] op_sel_hi:[1,0]
	s_mov_b64 exec, s[86:87]
	v_pk_mov_b32 v[76:77], v[76:77], v[78:79] op_sel:[1,0] op_sel_hi:[1,0]
	v_pk_mov_b32 v[78:79], v[78:79], v[70:71] op_sel:[1,0] op_sel_hi:[1,0]
	s_mov_b64 exec, s[88:89]
	v_pk_mov_b32 v[80:81], v[80:81], v[82:83] op_sel:[1,0] op_sel_hi:[1,0]
	v_pk_mov_b32 v[82:83], v[82:83], v[70:71] op_sel:[1,0] op_sel_hi:[1,0]
	s_mov_b64 exec, s[90:91]
	v_pk_mov_b32 v[84:85], v[84:85], v[86:87] op_sel:[1,0] op_sel_hi:[1,0]
	v_pk_mov_b32 v[86:87], v[86:87], v[70:71] op_sel:[1,0] op_sel_hi:[1,0]
	s_lshl_b64 exec, s[78:79], s40
	s_add_i32 s40, s40, 1
	v_pk_mov_b32 v[4:5], v[32:33], v[32:33] op_sel:[1,0] op_sel_hi:[1,0]
	v_pk_mov_b32 v[6:7], v[30:31], v[30:31] op_sel:[1,0] op_sel_hi:[1,0]
	s_mov_b64 exec, -1
	v_max_u32_dpp v31, v72, v72 row_ror:1 row_mask:0xf bank_mask:0xf bound_ctrl:1
	v_max_u32_dpp v30, v76, v76 row_ror:1 row_mask:0xf bank_mask:0xf bound_ctrl:1
	v_max_u32_dpp v32, v80, v80 row_ror:1 row_mask:0xf bank_mask:0xf bound_ctrl:1
	v_max_u32_dpp v31, v31, v31 row_ror:2 row_mask:0xf bank_mask:0xf bound_ctrl:1
	v_max_u32_dpp v33, v84, v84 row_ror:1 row_mask:0xf bank_mask:0xf bound_ctrl:1
	v_max_u32_dpp v30, v30, v30 row_ror:2 row_mask:0xf bank_mask:0xf bound_ctrl:1
	v_max_u32_dpp v32, v32, v32 row_ror:2 row_mask:0xf bank_mask:0xf bound_ctrl:1
	v_max_u32_dpp v31, v31, v31 row_ror:4 row_mask:0xf bank_mask:0xf bound_ctrl:1
	v_max_u32_dpp v33, v33, v33 row_ror:2 row_mask:0xf bank_mask:0xf bound_ctrl:1
	v_max_u32_dpp v30, v30, v30 row_ror:4 row_mask:0xf bank_mask:0xf bound_ctrl:1
	v_max_u32_dpp v32, v32, v32 row_ror:4 row_mask:0xf bank_mask:0xf bound_ctrl:1
	v_max_u32_dpp v31, v31, v31 row_ror:8 row_mask:0xf bank_mask:0xf bound_ctrl:1
	v_max_u32_dpp v33, v33, v33 row_ror:4 row_mask:0xf bank_mask:0xf bound_ctrl:1
	v_max_u32_dpp v30, v30, v30 row_ror:8 row_mask:0xf bank_mask:0xf bound_ctrl:1
	v_max_u32_dpp v32, v32, v32 row_ror:8 row_mask:0xf bank_mask:0xf bound_ctrl:1
	v_max_u32_dpp v33, v33, v33 row_ror:8 row_mask:0xf bank_mask:0xf bound_ctrl:1
	v_cmp_eq_u32_e64 s[84:85], v72, v31
	v_cmp_eq_u32_e64 s[86:87], v76, v30
	v_cmp_eq_u32_e64 s[88:89], v80, v32
	v_cmp_eq_u32_e64 s[90:91], v84, v33
	s_mov_b64 exec, s[84:85]
	v_pk_mov_b32 v[72:73], v[72:73], v[74:75] op_sel:[1,0] op_sel_hi:[1,0]
	v_pk_mov_b32 v[74:75], v[74:75], v[70:71] op_sel:[1,0] op_sel_hi:[1,0]
	s_mov_b64 exec, s[86:87]
	v_pk_mov_b32 v[76:77], v[76:77], v[78:79] op_sel:[1,0] op_sel_hi:[1,0]
	v_pk_mov_b32 v[78:79], v[78:79], v[70:71] op_sel:[1,0] op_sel_hi:[1,0]
	s_mov_b64 exec, s[88:89]
	v_pk_mov_b32 v[80:81], v[80:81], v[82:83] op_sel:[1,0] op_sel_hi:[1,0]
	v_pk_mov_b32 v[82:83], v[82:83], v[70:71] op_sel:[1,0] op_sel_hi:[1,0]
	s_mov_b64 exec, s[90:91]
	v_pk_mov_b32 v[84:85], v[84:85], v[86:87] op_sel:[1,0] op_sel_hi:[1,0]
	v_pk_mov_b32 v[86:87], v[86:87], v[70:71] op_sel:[1,0] op_sel_hi:[1,0]
	s_lshl_b64 exec, s[78:79], s40
	s_add_i32 s40, s40, 1
	v_pk_mov_b32 v[4:5], v[32:33], v[32:33] op_sel:[1,0] op_sel_hi:[1,0]
	v_pk_mov_b32 v[6:7], v[30:31], v[30:31] op_sel:[1,0] op_sel_hi:[1,0]
	s_mov_b64 exec, -1
	v_max_u32_dpp v31, v72, v72 row_ror:1 row_mask:0xf bank_mask:0xf bound_ctrl:1
	v_max_u32_dpp v30, v76, v76 row_ror:1 row_mask:0xf bank_mask:0xf bound_ctrl:1
	v_max_u32_dpp v32, v80, v80 row_ror:1 row_mask:0xf bank_mask:0xf bound_ctrl:1
	v_max_u32_dpp v31, v31, v31 row_ror:2 row_mask:0xf bank_mask:0xf bound_ctrl:1
	v_max_u32_dpp v33, v84, v84 row_ror:1 row_mask:0xf bank_mask:0xf bound_ctrl:1
	v_max_u32_dpp v30, v30, v30 row_ror:2 row_mask:0xf bank_mask:0xf bound_ctrl:1
	v_max_u32_dpp v32, v32, v32 row_ror:2 row_mask:0xf bank_mask:0xf bound_ctrl:1
	v_max_u32_dpp v31, v31, v31 row_ror:4 row_mask:0xf bank_mask:0xf bound_ctrl:1
	v_max_u32_dpp v33, v33, v33 row_ror:2 row_mask:0xf bank_mask:0xf bound_ctrl:1
	v_max_u32_dpp v30, v30, v30 row_ror:4 row_mask:0xf bank_mask:0xf bound_ctrl:1
	v_max_u32_dpp v32, v32, v32 row_ror:4 row_mask:0xf bank_mask:0xf bound_ctrl:1
	v_max_u32_dpp v31, v31, v31 row_ror:8 row_mask:0xf bank_mask:0xf bound_ctrl:1
	v_max_u32_dpp v33, v33, v33 row_ror:4 row_mask:0xf bank_mask:0xf bound_ctrl:1
	v_max_u32_dpp v30, v30, v30 row_ror:8 row_mask:0xf bank_mask:0xf bound_ctrl:1
	v_max_u32_dpp v32, v32, v32 row_ror:8 row_mask:0xf bank_mask:0xf bound_ctrl:1
	v_max_u32_dpp v33, v33, v33 row_ror:8 row_mask:0xf bank_mask:0xf bound_ctrl:1
	v_cmp_eq_u32_e64 s[84:85], v72, v31
	v_cmp_eq_u32_e64 s[86:87], v76, v30
	v_cmp_eq_u32_e64 s[88:89], v80, v32
	v_cmp_eq_u32_e64 s[90:91], v84, v33
	s_mov_b64 exec, s[84:85]
	v_pk_mov_b32 v[72:73], v[72:73], v[74:75] op_sel:[1,0] op_sel_hi:[1,0]
	v_pk_mov_b32 v[74:75], v[74:75], v[70:71] op_sel:[1,0] op_sel_hi:[1,0]
	s_mov_b64 exec, s[86:87]
	v_pk_mov_b32 v[76:77], v[76:77], v[78:79] op_sel:[1,0] op_sel_hi:[1,0]
	v_pk_mov_b32 v[78:79], v[78:79], v[70:71] op_sel:[1,0] op_sel_hi:[1,0]
	s_mov_b64 exec, s[88:89]
	v_pk_mov_b32 v[80:81], v[80:81], v[82:83] op_sel:[1,0] op_sel_hi:[1,0]
	v_pk_mov_b32 v[82:83], v[82:83], v[70:71] op_sel:[1,0] op_sel_hi:[1,0]
	s_mov_b64 exec, s[90:91]
	v_pk_mov_b32 v[84:85], v[84:85], v[86:87] op_sel:[1,0] op_sel_hi:[1,0]
	v_pk_mov_b32 v[86:87], v[86:87], v[70:71] op_sel:[1,0] op_sel_hi:[1,0]
	s_lshl_b64 exec, s[78:79], s40
	s_add_i32 s40, s40, 1
	v_pk_mov_b32 v[4:5], v[32:33], v[32:33] op_sel:[1,0] op_sel_hi:[1,0]
	v_pk_mov_b32 v[6:7], v[30:31], v[30:31] op_sel:[1,0] op_sel_hi:[1,0]
	s_mov_b64 exec, -1
	v_max_u32_dpp v31, v72, v72 row_ror:1 row_mask:0xf bank_mask:0xf bound_ctrl:1
	v_max_u32_dpp v30, v76, v76 row_ror:1 row_mask:0xf bank_mask:0xf bound_ctrl:1
	v_max_u32_dpp v32, v80, v80 row_ror:1 row_mask:0xf bank_mask:0xf bound_ctrl:1
	v_max_u32_dpp v31, v31, v31 row_ror:2 row_mask:0xf bank_mask:0xf bound_ctrl:1
	v_max_u32_dpp v33, v84, v84 row_ror:1 row_mask:0xf bank_mask:0xf bound_ctrl:1
	v_max_u32_dpp v30, v30, v30 row_ror:2 row_mask:0xf bank_mask:0xf bound_ctrl:1
	v_max_u32_dpp v32, v32, v32 row_ror:2 row_mask:0xf bank_mask:0xf bound_ctrl:1
	v_max_u32_dpp v31, v31, v31 row_ror:4 row_mask:0xf bank_mask:0xf bound_ctrl:1
	v_max_u32_dpp v33, v33, v33 row_ror:2 row_mask:0xf bank_mask:0xf bound_ctrl:1
	v_max_u32_dpp v30, v30, v30 row_ror:4 row_mask:0xf bank_mask:0xf bound_ctrl:1
	v_max_u32_dpp v32, v32, v32 row_ror:4 row_mask:0xf bank_mask:0xf bound_ctrl:1
	v_max_u32_dpp v31, v31, v31 row_ror:8 row_mask:0xf bank_mask:0xf bound_ctrl:1
	v_max_u32_dpp v33, v33, v33 row_ror:4 row_mask:0xf bank_mask:0xf bound_ctrl:1
	v_max_u32_dpp v30, v30, v30 row_ror:8 row_mask:0xf bank_mask:0xf bound_ctrl:1
	v_max_u32_dpp v32, v32, v32 row_ror:8 row_mask:0xf bank_mask:0xf bound_ctrl:1
	v_max_u32_dpp v33, v33, v33 row_ror:8 row_mask:0xf bank_mask:0xf bound_ctrl:1
	v_cmp_eq_u32_e64 s[84:85], v72, v31
	v_cmp_eq_u32_e64 s[86:87], v76, v30
	v_cmp_eq_u32_e64 s[88:89], v80, v32
	v_cmp_eq_u32_e64 s[90:91], v84, v33
	s_mov_b64 exec, s[84:85]
	v_pk_mov_b32 v[72:73], v[72:73], v[74:75] op_sel:[1,0] op_sel_hi:[1,0]
	v_pk_mov_b32 v[74:75], v[74:75], v[70:71] op_sel:[1,0] op_sel_hi:[1,0]
	s_mov_b64 exec, s[86:87]
	v_pk_mov_b32 v[76:77], v[76:77], v[78:79] op_sel:[1,0] op_sel_hi:[1,0]
	v_pk_mov_b32 v[78:79], v[78:79], v[70:71] op_sel:[1,0] op_sel_hi:[1,0]
	s_mov_b64 exec, s[88:89]
	v_pk_mov_b32 v[80:81], v[80:81], v[82:83] op_sel:[1,0] op_sel_hi:[1,0]
	v_pk_mov_b32 v[82:83], v[82:83], v[70:71] op_sel:[1,0] op_sel_hi:[1,0]
	s_mov_b64 exec, s[90:91]
	v_pk_mov_b32 v[84:85], v[84:85], v[86:87] op_sel:[1,0] op_sel_hi:[1,0]
	v_pk_mov_b32 v[86:87], v[86:87], v[70:71] op_sel:[1,0] op_sel_hi:[1,0]
	s_lshl_b64 exec, s[78:79], s40
	s_add_i32 s40, s40, 1
	v_pk_mov_b32 v[4:5], v[32:33], v[32:33] op_sel:[1,0] op_sel_hi:[1,0]
	v_pk_mov_b32 v[6:7], v[30:31], v[30:31] op_sel:[1,0] op_sel_hi:[1,0]
	s_mov_b64 exec, -1
	v_max_u32_dpp v31, v72, v72 row_ror:1 row_mask:0xf bank_mask:0xf bound_ctrl:1
	v_max_u32_dpp v30, v76, v76 row_ror:1 row_mask:0xf bank_mask:0xf bound_ctrl:1
	v_max_u32_dpp v32, v80, v80 row_ror:1 row_mask:0xf bank_mask:0xf bound_ctrl:1
	v_max_u32_dpp v31, v31, v31 row_ror:2 row_mask:0xf bank_mask:0xf bound_ctrl:1
	v_max_u32_dpp v33, v84, v84 row_ror:1 row_mask:0xf bank_mask:0xf bound_ctrl:1
	v_max_u32_dpp v30, v30, v30 row_ror:2 row_mask:0xf bank_mask:0xf bound_ctrl:1
	v_max_u32_dpp v32, v32, v32 row_ror:2 row_mask:0xf bank_mask:0xf bound_ctrl:1
	v_max_u32_dpp v31, v31, v31 row_ror:4 row_mask:0xf bank_mask:0xf bound_ctrl:1
	v_max_u32_dpp v33, v33, v33 row_ror:2 row_mask:0xf bank_mask:0xf bound_ctrl:1
	v_max_u32_dpp v30, v30, v30 row_ror:4 row_mask:0xf bank_mask:0xf bound_ctrl:1
	v_max_u32_dpp v32, v32, v32 row_ror:4 row_mask:0xf bank_mask:0xf bound_ctrl:1
	v_max_u32_dpp v31, v31, v31 row_ror:8 row_mask:0xf bank_mask:0xf bound_ctrl:1
	v_max_u32_dpp v33, v33, v33 row_ror:4 row_mask:0xf bank_mask:0xf bound_ctrl:1
	v_max_u32_dpp v30, v30, v30 row_ror:8 row_mask:0xf bank_mask:0xf bound_ctrl:1
	v_max_u32_dpp v32, v32, v32 row_ror:8 row_mask:0xf bank_mask:0xf bound_ctrl:1
	v_max_u32_dpp v33, v33, v33 row_ror:8 row_mask:0xf bank_mask:0xf bound_ctrl:1
	v_cmp_eq_u32_e64 s[84:85], v72, v31
	v_cmp_eq_u32_e64 s[86:87], v76, v30
	v_cmp_eq_u32_e64 s[88:89], v80, v32
	v_cmp_eq_u32_e64 s[90:91], v84, v33
	s_mov_b64 exec, s[84:85]
	v_pk_mov_b32 v[72:73], v[72:73], v[74:75] op_sel:[1,0] op_sel_hi:[1,0]
	v_pk_mov_b32 v[74:75], v[74:75], v[70:71] op_sel:[1,0] op_sel_hi:[1,0]
	s_mov_b64 exec, s[86:87]
	v_pk_mov_b32 v[76:77], v[76:77], v[78:79] op_sel:[1,0] op_sel_hi:[1,0]
	v_pk_mov_b32 v[78:79], v[78:79], v[70:71] op_sel:[1,0] op_sel_hi:[1,0]
	s_mov_b64 exec, s[88:89]
	v_pk_mov_b32 v[80:81], v[80:81], v[82:83] op_sel:[1,0] op_sel_hi:[1,0]
	v_pk_mov_b32 v[82:83], v[82:83], v[70:71] op_sel:[1,0] op_sel_hi:[1,0]
	s_mov_b64 exec, s[90:91]
	v_pk_mov_b32 v[84:85], v[84:85], v[86:87] op_sel:[1,0] op_sel_hi:[1,0]
	v_pk_mov_b32 v[86:87], v[86:87], v[70:71] op_sel:[1,0] op_sel_hi:[1,0]
	s_lshl_b64 exec, s[78:79], s40
	s_add_i32 s40, s40, 1
	v_pk_mov_b32 v[4:5], v[32:33], v[32:33] op_sel:[1,0] op_sel_hi:[1,0]
	v_pk_mov_b32 v[6:7], v[30:31], v[30:31] op_sel:[1,0] op_sel_hi:[1,0]
	s_mov_b64 exec, -1
	v_max_u32_dpp v31, v72, v72 row_ror:1 row_mask:0xf bank_mask:0xf bound_ctrl:1
	v_max_u32_dpp v30, v76, v76 row_ror:1 row_mask:0xf bank_mask:0xf bound_ctrl:1
	v_max_u32_dpp v32, v80, v80 row_ror:1 row_mask:0xf bank_mask:0xf bound_ctrl:1
	v_max_u32_dpp v31, v31, v31 row_ror:2 row_mask:0xf bank_mask:0xf bound_ctrl:1
	v_max_u32_dpp v33, v84, v84 row_ror:1 row_mask:0xf bank_mask:0xf bound_ctrl:1
	v_max_u32_dpp v30, v30, v30 row_ror:2 row_mask:0xf bank_mask:0xf bound_ctrl:1
	v_max_u32_dpp v32, v32, v32 row_ror:2 row_mask:0xf bank_mask:0xf bound_ctrl:1
	v_max_u32_dpp v31, v31, v31 row_ror:4 row_mask:0xf bank_mask:0xf bound_ctrl:1
	v_max_u32_dpp v33, v33, v33 row_ror:2 row_mask:0xf bank_mask:0xf bound_ctrl:1
	v_max_u32_dpp v30, v30, v30 row_ror:4 row_mask:0xf bank_mask:0xf bound_ctrl:1
	v_max_u32_dpp v32, v32, v32 row_ror:4 row_mask:0xf bank_mask:0xf bound_ctrl:1
	v_max_u32_dpp v31, v31, v31 row_ror:8 row_mask:0xf bank_mask:0xf bound_ctrl:1
	v_max_u32_dpp v33, v33, v33 row_ror:4 row_mask:0xf bank_mask:0xf bound_ctrl:1
	v_max_u32_dpp v30, v30, v30 row_ror:8 row_mask:0xf bank_mask:0xf bound_ctrl:1
	v_max_u32_dpp v32, v32, v32 row_ror:8 row_mask:0xf bank_mask:0xf bound_ctrl:1
	v_max_u32_dpp v33, v33, v33 row_ror:8 row_mask:0xf bank_mask:0xf bound_ctrl:1
	v_cmp_eq_u32_e64 s[84:85], v72, v31
	v_cmp_eq_u32_e64 s[86:87], v76, v30
	v_cmp_eq_u32_e64 s[88:89], v80, v32
	v_cmp_eq_u32_e64 s[90:91], v84, v33
	s_mov_b64 exec, s[84:85]
	v_pk_mov_b32 v[72:73], v[72:73], v[74:75] op_sel:[1,0] op_sel_hi:[1,0]
	s_mov_b64 exec, s[86:87]
	v_pk_mov_b32 v[76:77], v[76:77], v[78:79] op_sel:[1,0] op_sel_hi:[1,0]
	s_mov_b64 exec, s[88:89]
	v_pk_mov_b32 v[80:81], v[80:81], v[82:83] op_sel:[1,0] op_sel_hi:[1,0]
	s_mov_b64 exec, s[90:91]
	v_pk_mov_b32 v[84:85], v[84:85], v[86:87] op_sel:[1,0] op_sel_hi:[1,0]
	s_lshl_b64 exec, s[78:79], s40
	s_add_i32 s40, s40, 1
	v_pk_mov_b32 v[4:5], v[32:33], v[32:33] op_sel:[1,0] op_sel_hi:[1,0]
	v_pk_mov_b32 v[6:7], v[30:31], v[30:31] op_sel:[1,0] op_sel_hi:[1,0]
	s_mov_b64 exec, -1
	v_max_u32_dpp v31, v72, v72 row_ror:1 row_mask:0xf bank_mask:0xf bound_ctrl:1
	v_max_u32_dpp v30, v76, v76 row_ror:1 row_mask:0xf bank_mask:0xf bound_ctrl:1
	v_max_u32_dpp v32, v80, v80 row_ror:1 row_mask:0xf bank_mask:0xf bound_ctrl:1
	v_max_u32_dpp v31, v31, v31 row_ror:2 row_mask:0xf bank_mask:0xf bound_ctrl:1
	v_max_u32_dpp v33, v84, v84 row_ror:1 row_mask:0xf bank_mask:0xf bound_ctrl:1
	v_max_u32_dpp v30, v30, v30 row_ror:2 row_mask:0xf bank_mask:0xf bound_ctrl:1
	v_max_u32_dpp v32, v32, v32 row_ror:2 row_mask:0xf bank_mask:0xf bound_ctrl:1
	v_max_u32_dpp v31, v31, v31 row_ror:4 row_mask:0xf bank_mask:0xf bound_ctrl:1
	v_max_u32_dpp v33, v33, v33 row_ror:2 row_mask:0xf bank_mask:0xf bound_ctrl:1
	v_max_u32_dpp v30, v30, v30 row_ror:4 row_mask:0xf bank_mask:0xf bound_ctrl:1
	v_max_u32_dpp v32, v32, v32 row_ror:4 row_mask:0xf bank_mask:0xf bound_ctrl:1
	v_max_u32_dpp v31, v31, v31 row_ror:8 row_mask:0xf bank_mask:0xf bound_ctrl:1
	v_max_u32_dpp v33, v33, v33 row_ror:4 row_mask:0xf bank_mask:0xf bound_ctrl:1
	v_max_u32_dpp v30, v30, v30 row_ror:8 row_mask:0xf bank_mask:0xf bound_ctrl:1
	v_max_u32_dpp v32, v32, v32 row_ror:8 row_mask:0xf bank_mask:0xf bound_ctrl:1
	v_max_u32_dpp v33, v33, v33 row_ror:8 row_mask:0xf bank_mask:0xf bound_ctrl:1
	v_cmp_eq_u32_e64 s[84:85], v72, v31
	v_cmp_eq_u32_e64 s[86:87], v76, v30
	v_cmp_eq_u32_e64 s[88:89], v80, v32
	v_cmp_eq_u32_e64 s[90:91], v84, v33
	s_mov_b64 exec, s[84:85]
	v_pk_mov_b32 v[72:73], v[72:73], v[74:75] op_sel:[1,0] op_sel_hi:[1,0]
	s_mov_b64 exec, s[86:87]
	v_pk_mov_b32 v[76:77], v[76:77], v[78:79] op_sel:[1,0] op_sel_hi:[1,0]
	s_mov_b64 exec, s[88:89]
	v_pk_mov_b32 v[80:81], v[80:81], v[82:83] op_sel:[1,0] op_sel_hi:[1,0]
	s_mov_b64 exec, s[90:91]
	v_pk_mov_b32 v[84:85], v[84:85], v[86:87] op_sel:[1,0] op_sel_hi:[1,0]
	s_lshl_b64 exec, s[78:79], s40
	s_add_i32 s40, s40, 1
	v_pk_mov_b32 v[4:5], v[32:33], v[32:33] op_sel:[1,0] op_sel_hi:[1,0]
	v_pk_mov_b32 v[6:7], v[30:31], v[30:31] op_sel:[1,0] op_sel_hi:[1,0]
	s_mov_b64 exec, -1
	v_max_u32_dpp v31, v72, v72 row_ror:1 row_mask:0xf bank_mask:0xf bound_ctrl:1
	v_max_u32_dpp v30, v76, v76 row_ror:1 row_mask:0xf bank_mask:0xf bound_ctrl:1
	v_max_u32_dpp v32, v80, v80 row_ror:1 row_mask:0xf bank_mask:0xf bound_ctrl:1
	v_max_u32_dpp v31, v31, v31 row_ror:2 row_mask:0xf bank_mask:0xf bound_ctrl:1
	v_max_u32_dpp v33, v84, v84 row_ror:1 row_mask:0xf bank_mask:0xf bound_ctrl:1
	v_max_u32_dpp v30, v30, v30 row_ror:2 row_mask:0xf bank_mask:0xf bound_ctrl:1
	v_max_u32_dpp v32, v32, v32 row_ror:2 row_mask:0xf bank_mask:0xf bound_ctrl:1
	v_max_u32_dpp v31, v31, v31 row_ror:4 row_mask:0xf bank_mask:0xf bound_ctrl:1
	v_max_u32_dpp v33, v33, v33 row_ror:2 row_mask:0xf bank_mask:0xf bound_ctrl:1
	v_max_u32_dpp v30, v30, v30 row_ror:4 row_mask:0xf bank_mask:0xf bound_ctrl:1
	v_max_u32_dpp v32, v32, v32 row_ror:4 row_mask:0xf bank_mask:0xf bound_ctrl:1
	v_max_u32_dpp v31, v31, v31 row_ror:8 row_mask:0xf bank_mask:0xf bound_ctrl:1
	v_max_u32_dpp v33, v33, v33 row_ror:4 row_mask:0xf bank_mask:0xf bound_ctrl:1
	v_max_u32_dpp v30, v30, v30 row_ror:8 row_mask:0xf bank_mask:0xf bound_ctrl:1
	v_max_u32_dpp v32, v32, v32 row_ror:8 row_mask:0xf bank_mask:0xf bound_ctrl:1
	v_max_u32_dpp v33, v33, v33 row_ror:8 row_mask:0xf bank_mask:0xf bound_ctrl:1
	s_lshl_b64 exec, s[78:79], s40
	v_pk_mov_b32 v[4:5], v[32:33], v[32:33] op_sel:[1,0] op_sel_hi:[1,0]
	v_pk_mov_b32 v[6:7], v[30:31], v[30:31] op_sel:[1,0] op_sel_hi:[1,0]
	s_mov_b64 exec, -1
	v_max_u32_dpp v15, v7, v7 row_ror:1 row_mask:0xf bank_mask:0xf bound_ctrl:1
	v_cmp_lt_i32_e32 vcc, -1, v7
	v_bitop3_b32 v11, v18, s60, v18 bitop3:0xc
	v_max_u32_dpp v15, v15, v15 row_ror:2 row_mask:0xf bank_mask:0xf bound_ctrl:1
	v_cndmask_b32_e64 v14, v217, -1, vcc
	v_bitop3_b32 v14, v14, v7, s59 bitop3:0x78
	v_max_u32_dpp v15, v15, v15 row_ror:4 row_mask:0xf bank_mask:0xf bound_ctrl:1
	v_not_b32_e32 v13, v7
	v_lshrrev_b32_e32 v13, 4, v13
	v_max_u32_dpp v15, v15, v15 row_ror:8 row_mask:0xf bank_mask:0xf bound_ctrl:1
	v_cmp_lt_i32_e32 vcc, -1, v15
	v_and_or_b32 v13, v13, 15, v195
	v_lshlrev_b32_e32 v13, 2, v13
	v_cndmask_b32_e64 v18, v217, -1, vcc
	v_bitop3_b32 v15, v18, v15, s59 bitop3:0x78
	v_sub_f32_e32 v14, v14, v15
	v_mul_f32_e32 v14, 0x3fb8aa3b, v14
	v_exp_f32_e32 v14, v14
	ds_bpermute_b32 v11, v13, v11
	v_bitop3_b32 v7, v7, v195, 15 bitop3:0xce
	v_bitop3_b32 v0, v0, s60, v0 bitop3:0xc
	v_add_f32_dpp v13, v14, v14 row_ror:1 row_mask:0xf bank_mask:0xf bound_ctrl:1
	v_lshlrev_b32_e32 v7, 2, v7
	ds_bpermute_b32 v0, v7, v0
	v_add_f32_dpp v13, v13, v13 row_ror:2 row_mask:0xf bank_mask:0xf bound_ctrl:1
	v_bitop3_b32 v10, v19, s60, v19 bitop3:0xc
	v_bitop3_b32 v9, v20, s60, v20 bitop3:0xc
	v_add_f32_dpp v13, v13, v13 row_ror:4 row_mask:0xf bank_mask:0xf bound_ctrl:1
	v_lshl_or_b32 v12, s33, 4, v171
	s_waitcnt lgkmcnt(0)
	v_lshl_add_u32 v0, v11, 7, v0
	v_add_f32_dpp v13, v13, v13 row_ror:8 row_mask:0xf bank_mask:0xf bound_ctrl:1
	v_div_scale_f32 v15, s[0:1], v13, v13, v14
	v_rcp_f32_e32 v18, v15
	v_bitop3_b32 v1, v1, s60, v1 bitop3:0xc
	v_bitop3_b32 v2, v2, s60, v2 bitop3:0xc
	v_bitop3_b32 v3, v3, s60, v3 bitop3:0xc
	v_fma_f32 v7, -v15, v18, 1.0
	v_fmac_f32_e32 v18, v7, v18
	v_div_scale_f32 v7, vcc, v14, v13, v14
	v_mul_f32_e32 v19, v7, v18
	v_fma_f32 v20, -v15, v19, v7
	v_fmac_f32_e32 v19, v20, v18
	v_fma_f32 v7, -v15, v19, v7
	v_div_fmas_f32 v7, v7, v18, v19
	v_div_fixup_f32 v7, v7, v13, v14
	v_or_b32_e32 v13, v12, v183
	v_lshl_add_u32 v11, v13, 1, s63
	v_cvt_f16_f32_e32 v7, v7
	v_max_u32_dpp v13, v6, v6 row_ror:1 row_mask:0xf bank_mask:0xf bound_ctrl:1
	v_cmp_lt_i32_e32 vcc, -1, v6
	ds_write_b16 v11, v0
	ds_write_b16 v11, v7 offset:32768
	v_max_u32_dpp v13, v13, v13 row_ror:2 row_mask:0xf bank_mask:0xf bound_ctrl:1
	v_cndmask_b32_e64 v7, v217, -1, vcc
	v_bitop3_b32 v7, v7, v6, s59 bitop3:0x78
	v_max_u32_dpp v13, v13, v13 row_ror:4 row_mask:0xf bank_mask:0xf bound_ctrl:1
	v_not_b32_e32 v0, v6
	v_lshrrev_b32_e32 v0, 4, v0
	v_max_u32_dpp v13, v13, v13 row_ror:8 row_mask:0xf bank_mask:0xf bound_ctrl:1
	v_cmp_lt_i32_e32 vcc, -1, v13
	v_and_or_b32 v0, v0, 15, v195
	v_lshlrev_b32_e32 v0, 2, v0
	v_cndmask_b32_e64 v14, v217, -1, vcc
	v_bitop3_b32 v13, v14, v13, s59 bitop3:0x78
	v_sub_f32_e32 v7, v7, v13
	v_mul_f32_e32 v7, 0x3fb8aa3b, v7
	v_exp_f32_e32 v7, v7
	ds_bpermute_b32 v0, v0, v10
	v_bitop3_b32 v6, v6, v195, 15 bitop3:0xce
	v_lshlrev_b32_e32 v6, 2, v6
	v_add_f32_dpp v10, v7, v7 row_ror:1 row_mask:0xf bank_mask:0xf bound_ctrl:1
	ds_bpermute_b32 v1, v6, v1
	v_bitop3_b32 v8, v21, s60, v21 bitop3:0xc
	v_add_f32_dpp v10, v10, v10 row_ror:2 row_mask:0xf bank_mask:0xf bound_ctrl:1
	s_waitcnt lgkmcnt(0)
	v_lshl_add_u32 v0, v0, 7, v1
	v_add_f32_dpp v10, v10, v10 row_ror:4 row_mask:0xf bank_mask:0xf bound_ctrl:1
	ds_write_b16 v11, v0 offset:256
	v_not_b32_e32 v1, v5
	v_add_f32_dpp v10, v10, v10 row_ror:8 row_mask:0xf bank_mask:0xf bound_ctrl:1
	v_div_scale_f32 v13, s[0:1], v10, v10, v7
	v_rcp_f32_e32 v14, v13
	v_lshrrev_b32_e32 v1, 4, v1
	v_and_or_b32 v1, v1, 15, v195
	v_lshlrev_b32_e32 v1, 2, v1
	v_fma_f32 v6, -v13, v14, 1.0
	v_fmac_f32_e32 v14, v6, v14
	v_div_scale_f32 v6, vcc, v7, v10, v7
	v_mul_f32_e32 v15, v6, v14
	v_fma_f32 v18, -v13, v15, v6
	v_fmac_f32_e32 v15, v18, v14
	v_fma_f32 v6, -v13, v15, v6
	v_div_fmas_f32 v6, v6, v14, v15
	v_div_fixup_f32 v6, v6, v10, v7
	v_max_u32_dpp v7, v5, v5 row_ror:1 row_mask:0xf bank_mask:0xf bound_ctrl:1
	v_cmp_lt_i32_e32 vcc, -1, v5
	v_cvt_f16_f32_e32 v0, v6
	v_max_u32_dpp v7, v7, v7 row_ror:2 row_mask:0xf bank_mask:0xf bound_ctrl:1
	v_cndmask_b32_e64 v6, v217, -1, vcc
	v_bitop3_b32 v6, v6, v5, s59 bitop3:0x78
	v_max_u32_dpp v7, v7, v7 row_ror:4 row_mask:0xf bank_mask:0xf bound_ctrl:1
	ds_bpermute_b32 v1, v1, v9
	v_bitop3_b32 v5, v5, v195, 15 bitop3:0xce
	v_max_u32_dpp v7, v7, v7 row_ror:8 row_mask:0xf bank_mask:0xf bound_ctrl:1
	v_cmp_lt_i32_e32 vcc, -1, v7
	v_lshlrev_b32_e32 v5, 2, v5
	ds_bpermute_b32 v2, v5, v2
	v_cndmask_b32_e64 v10, v217, -1, vcc
	v_bitop3_b32 v7, v10, v7, s59 bitop3:0x78
	v_sub_f32_e32 v6, v6, v7
	v_mul_f32_e32 v6, 0x3fb8aa3b, v6
	v_exp_f32_e32 v6, v6
	ds_write_b16 v11, v0 offset:33024
	s_waitcnt lgkmcnt(1)
	v_lshl_add_u32 v0, v1, 7, v2
	v_max_u32_dpp v2, v4, v4 row_ror:1 row_mask:0xf bank_mask:0xf bound_ctrl:1
	v_add_f32_dpp v7, v6, v6 row_ror:1 row_mask:0xf bank_mask:0xf bound_ctrl:1
	s_nop 0
	v_max_u32_dpp v2, v2, v2 row_ror:2 row_mask:0xf bank_mask:0xf bound_ctrl:1
	v_add_f32_dpp v7, v7, v7 row_ror:2 row_mask:0xf bank_mask:0xf bound_ctrl:1
	s_nop 0
	v_max_u32_dpp v2, v2, v2 row_ror:4 row_mask:0xf bank_mask:0xf bound_ctrl:1
	v_add_f32_dpp v7, v7, v7 row_ror:4 row_mask:0xf bank_mask:0xf bound_ctrl:1
	s_nop 0
	v_max_u32_dpp v2, v2, v2 row_ror:8 row_mask:0xf bank_mask:0xf bound_ctrl:1
	v_add_f32_dpp v7, v7, v7 row_ror:8 row_mask:0xf bank_mask:0xf bound_ctrl:1
	v_div_scale_f32 v9, s[0:1], v7, v7, v6
	v_rcp_f32_e32 v10, v9
	s_nop 0
	v_fma_f32 v5, -v9, v10, 1.0
	v_fmac_f32_e32 v10, v5, v10
	v_div_scale_f32 v5, vcc, v6, v7, v6
	v_mul_f32_e32 v13, v5, v10
	v_fma_f32 v14, -v9, v13, v5
	v_fmac_f32_e32 v13, v14, v10
	v_fma_f32 v5, -v9, v13, v5
	v_div_fmas_f32 v5, v5, v10, v13
	v_div_fixup_f32 v5, v5, v7, v6
	v_cvt_f16_f32_e32 v5, v5
	v_cmp_lt_i32_e32 vcc, -1, v4
	ds_write_b16 v11, v0 offset:512
	ds_write_b16 v11, v5 offset:33280
	v_cndmask_b32_e64 v1, v217, -1, vcc
	v_cmp_lt_i32_e32 vcc, -1, v2
	v_bitop3_b32 v1, v1, v4, s59 bitop3:0x78
	v_not_b32_e32 v0, v4
	v_cndmask_b32_e64 v5, v217, -1, vcc
	v_bitop3_b32 v2, v5, v2, s59 bitop3:0x78
	v_sub_f32_e32 v1, v1, v2
	v_mul_f32_e32 v1, 0x3fb8aa3b, v1
	v_exp_f32_e32 v1, v1
	v_bitop3_b32 v4, v4, v195, 15 bitop3:0xce
	v_lshlrev_b32_e32 v4, 2, v4
	v_lshrrev_b32_e32 v0, 4, v0
	v_add_f32_dpp v2, v1, v1 row_ror:1 row_mask:0xf bank_mask:0xf bound_ctrl:1
	ds_bpermute_b32 v3, v4, v3
	v_and_or_b32 v0, v0, 15, v195
	v_add_f32_dpp v2, v2, v2 row_ror:2 row_mask:0xf bank_mask:0xf bound_ctrl:1
	v_lshlrev_b32_e32 v0, 2, v0
	ds_bpermute_b32 v0, v0, v8
	v_add_f32_dpp v2, v2, v2 row_ror:4 row_mask:0xf bank_mask:0xf bound_ctrl:1
	s_waitcnt lgkmcnt(0)
	v_lshl_add_u32 v0, v0, 7, v3
	v_add_f32_dpp v2, v2, v2 row_ror:8 row_mask:0xf bank_mask:0xf bound_ctrl:1
	v_div_scale_f32 v5, s[0:1], v2, v2, v1
	v_rcp_f32_e32 v6, v5
	s_add_i32 s0, s33, 1
	s_cmp_lg_u32 s33, 7
	s_cselect_b32 s1, s0, 7
	v_fma_f32 v4, -v5, v6, 1.0
	v_fmac_f32_e32 v6, v4, v6
	v_div_scale_f32 v4, vcc, v1, v2, v1
	v_mul_f32_e32 v7, v4, v6
	v_fma_f32 v8, -v5, v7, v4
	v_fmac_f32_e32 v7, v8, v6
	v_fma_f32 v4, -v5, v7, v4
	v_div_fmas_f32 v4, v4, v6, v7
	v_div_fixup_f32 v1, v4, v2, v1
	v_add_u32_e32 v2, v12, v182
	v_cvt_f16_f32_e32 v1, v1
	v_lshl_or_b32 v2, v2, 1, v218
	s_lshl_b32 s40, s1, 16
	v_add_u32_e32 v2, s63, v2
	s_cmp_lt_u32 s1, 4
	ds_write_b16 v2, v0
	ds_write_b16 v2, v1 offset:32768
	v_lshl_add_u64 v[0:1], v[154:155], 0, s[40:41]
	s_cselect_b32 s33, s3, s56
	s_cselect_b32 s40, s2, s55
	v_mov_b32_e32 v2, s40
	v_mov_b32_e32 v3, s33
	s_lshl_b32 s1, s1, 9
	v_lshl_add_u64 v[2:3], v[16:17], 1, v[2:3]
	s_and_b32 s40, s1, 0x600
	v_lshl_add_u64 v[2:3], v[2:3], 0, s[40:41]
	v_lshl_add_u64 v[12:13], v[2:3], 0, v[148:149]
	s_cmp_eq_u32 s0, 8
	s_mov_b32 s33, s0
	s_cbranch_scc0 .LBB0_1346
	s_setprio 0
	s_waitcnt lgkmcnt(0)
	s_barrier
	ds_read_b128 v[0:3], v185
	ds_read_b128 v[40:43], v185 offset:16
	s_ashr_i32 s49, s48, 31
	s_lshl_b64 s[0:1], s[48:49], 10
	v_lshl_add_u64 v[144:145], v[152:153], 0, s[0:1]
	s_waitcnt lgkmcnt(1)
	v_lshlrev_b32_e32 v4, 7, v0
	v_mad_u32_u16 v0, v0, s81, v150 op_sel:[1,0,0,0]
	v_and_or_b32 v64, v4, s68, v150
	v_mad_u32_u16 v4, v1, s81, v150
	global_load_dwordx4 v[60:63], v0, s[26:27]
	global_load_dwordx4 v[56:59], v4, s[26:27]
	v_mad_u32_u16 v0, v1, s81, v150 op_sel:[1,0,0,0]
	v_mad_u32_u16 v1, v2, s81, v150
	global_load_dwordx4 v[52:55], v0, s[26:27]
	global_load_dwordx4 v[48:51], v1, s[26:27]
	v_mad_u32_u16 v0, v2, s81, v150 op_sel:[1,0,0,0]
	v_mad_u32_u16 v1, v3, s81, v150
	global_load_dwordx4 v[44:47], v0, s[26:27]
	global_load_dwordx4 v[36:39], v1, s[26:27]
	v_mad_u32_u16 v0, v3, s81, v150 op_sel:[1,0,0,0]
	s_waitcnt lgkmcnt(0)
	v_mad_u32_u16 v1, v40, s81, v150
	global_load_dwordx4 v[32:35], v0, s[26:27]
	global_load_dwordx4 v[28:31], v1, s[26:27]
	v_mad_u32_u16 v0, v40, s81, v150 op_sel:[1,0,0,0]
	v_mad_u32_u16 v1, v41, s81, v150
	global_load_dwordx4 v[24:27], v0, s[26:27]
	global_load_dwordx4 v[20:23], v1, s[26:27]
	v_mad_u32_u16 v0, v41, s81, v150 op_sel:[1,0,0,0]
	v_mad_u32_u16 v1, v42, s81, v150
	global_load_dwordx4 v[16:19], v0, s[26:27]
	global_load_dwordx4 v[12:15], v1, s[26:27]
	v_mad_u32_u16 v0, v42, s81, v150 op_sel:[1,0,0,0]
	v_mad_u32_u16 v1, v43, s81, v150
	global_load_dwordx4 v[8:11], v0, s[26:27]
	global_load_dwordx4 v[4:7], v1, s[26:27]
	v_mad_u32_u16 v0, v43, s81, v150 op_sel:[1,0,0,0]
	global_load_dwordx4 v[0:3], v0, s[26:27]
	s_nop 0
	global_load_dwordx4 v[64:67], v64, s[26:27]
	s_nop 0
	global_load_dwordx4 v[40:43], v[144:145], off
	ds_read_b128 v[140:143], v185 offset:256
	ds_read_b128 v[136:139], v185 offset:272
	s_mov_b32 s76, 0
	s_branch .LBB0_1379
